# P4 task-table cost weights NSA:DSA 25:24 (NSA steps ~15% cheaper than when 7:6 was set)
# baseline (speedup 1.0000x reference)
; __global__ void __launch_bounds__(NTHR, 2) fwd_kernel(Args a) {
;     ...
;             for (int k = lane; k < 96; k += 64) {
;                 const int cost = k < 32 ? 7 * ((k + 1) + (k + 1 < 9 ? k + 1 : 9)) : 6 * (((k - 32) >> 1) + 1), cnt = k < 32 ? 32 : 16; int pos = 0;
;                 for (int k2 = 0; k2 < 96; ++k2) { const int c2 = k2 < 32 ? 7 * ((k2 + 1) + (k2 + 1 < 9 ? k2 + 1 : 9)) : 6 * (((k2 - 32) >> 1) + 1), n2 = k2 < 32 ? 32 : 16;
;                     if (c2 > cost || (c2 == cost && k2 < k)) pos += n2; }
;                 for (int bb = 0; bb < cnt; ++bb) TASKTAB[pos + bb] = (unsigned)k | ((unsigned)bb << 8);
;             }
.LBB0_159:
	v_cmp_lt_u32_e32 vcc, 31, v2
	s_and_saveexec_b64 s[4:5], vcc
	s_xor_b64 s[4:5], exec, s[4:5]
	v_subrev_u32_e32 v1, 32, v2
	v_lshrrev_b32_e32 v1, 1, v1
	v_mad_u64_u32 v[4:5], s[6:7], v1, 24, 24
	s_or_saveexec_b64 s[4:5], s[4:5]
	v_mov_b32_e32 v6, 16
	s_xor_b64 exec, exec, s[4:5]
	v_add_u32_e32 v1, 1, v2
	v_min_u32_e32 v3, 9, v1
	v_add_u32_e32 v1, v3, v1
	v_mul_lo_u32 v4, v1, 25
	v_mov_b32_e32 v6, 32
	s_or_b64 exec, exec, s[4:5]
	s_and_b64 s[4:5], exec, vcc
	s_or_b64 s[22:23], s[4:5], s[22:23]
	v_mov_b32_e32 v3, v4
	v_mov_b32_e32 v1, v2
	s_mov_b32 s21, 1
	v_mov_b32_e32 v7, 0
	s_movk_i32 s30, 0x60
	s_mov_b32 s31, 0
	v_mov_b32_e32 v5, 0
.LBB0_164:
	s_sub_i32 s6, s31, 32
	s_sub_i32 s7, s21, 32
	s_add_i32 s8, s21, 1
	s_add_i32 s9, s31, 1
	s_lshr_b32 s7, s7, 1
	s_lshr_b32 s6, s6, 1
	s_min_u32 s10, s9, 9
	s_min_u32 s11, s8, 9
	s_mul_i32 s6, s6, 24
	s_mul_i32 s7, s7, 24
	s_add_i32 s8, s11, s8
	s_add_i32 s9, s10, s9
	s_add_i32 s7, s7, 24
	s_add_i32 s6, s6, 24
	s_mul_i32 s9, s9, 25
	s_cmp_lt_u32 s31, 32
	s_mul_i32 s8, s8, 25
	s_cselect_b32 s10, 32, 16
	s_cselect_b32 s9, s9, s6
	s_cmp_lt_u32 s21, 32
	v_cmp_ge_u32_e32 vcc, s31, v2
	s_cselect_b32 s12, s8, s7
	v_cmp_le_i32_e64 s[6:7], s9, v4
	v_cmp_ne_u32_e64 s[8:9], s9, v4
	s_cselect_b32 s33, 32, 16
	s_sub_i32 s40, s21, 30
	s_sub_i32 s41, s31, 30
	s_or_b64 s[34:35], s[8:9], vcc
	v_cmp_ge_u32_e64 s[4:5], s21, v1
	v_mov_b32_e32 v8, s10
	s_add_i32 s46, s31, 3
	s_add_i32 s47, s21, 3
	v_cmp_le_i32_e64 s[10:11], s12, v3
	v_cmp_ne_u32_e64 s[12:13], s12, v3
	v_mov_b32_e32 v9, s33
	s_lshr_b32 s33, s41, 1
	s_lshr_b32 s40, s40, 1
	s_and_b64 s[6:7], s[6:7], s[34:35]
	s_min_u32 s41, s47, 9
	s_min_u32 s48, s46, 9
	s_or_b64 s[4:5], s[12:13], s[4:5]
	v_cndmask_b32_e64 v8, v8, 0, s[6:7]
	s_mul_i32 s6, s40, 24
	s_mul_i32 s7, s33, 24
	s_add_i32 s36, s31, 2
	s_add_i32 s37, s21, 2
	s_add_i32 s12, s48, s46
	s_add_i32 s13, s41, s47
	s_and_b64 s[4:5], s[10:11], s[4:5]
	s_add_i32 s7, s7, 24
	s_add_i32 s6, s6, 24
	s_mul_i32 s13, s13, 25
	s_cmp_lt_u32 s37, 32
	s_mul_i32 s12, s12, 25
	s_cselect_b32 s10, 32, 16
	s_cselect_b32 s6, s13, s6
	s_cmp_lt_u32 s36, 32
	v_cmp_ge_u32_e32 vcc, s37, v1
	v_cndmask_b32_e64 v9, v9, 0, s[4:5]
	s_cselect_b32 s33, 32, 16
	s_cselect_b32 s12, s12, s7
	v_cmp_le_i32_e64 s[4:5], s6, v3
	v_cmp_ne_u32_e64 s[6:7], s6, v3
	s_sub_i32 s40, s21, 28
	s_sub_i32 s41, s31, 28
	v_cmp_ge_u32_e64 s[8:9], s36, v2
	v_add_u32_e32 v7, v7, v8
	v_add_u32_e32 v5, v5, v9
	v_mov_b32_e32 v8, s10
	s_add_i32 s46, s31, 5
	s_add_i32 s47, s21, 5
	v_cmp_le_i32_e64 s[10:11], s12, v4
	v_cmp_ne_u32_e64 s[12:13], s12, v4
	s_or_b64 s[34:35], s[6:7], vcc
	v_mov_b32_e32 v9, s33
	s_lshr_b32 s33, s41, 1
	s_lshr_b32 s40, s40, 1
	s_min_u32 s41, s47, 9
	s_min_u32 s48, s46, 9
	s_or_b64 s[8:9], s[12:13], s[8:9]
	s_and_b64 s[4:5], s[4:5], s[34:35]
	s_mul_i32 s12, s40, 24
	s_mul_i32 s13, s33, 24
	s_add_i32 s36, s31, 4
	s_add_i32 s37, s21, 4
	v_cndmask_b32_e64 v8, v8, 0, s[4:5]
	s_add_i32 s33, s48, s46
	s_add_i32 s34, s41, s47
	s_and_b64 s[4:5], s[10:11], s[8:9]
	s_add_i32 s13, s13, 24
	s_add_i32 s12, s12, 24
	s_mul_i32 s34, s34, 25
	s_cmp_lt_u32 s37, 32
	s_mul_i32 s33, s33, 25
	s_cselect_b32 s10, 32, 16
	s_cselect_b32 s8, s34, s12
	s_cmp_lt_u32 s36, 32
	v_cmp_ge_u32_e32 vcc, s37, v1
	v_cndmask_b32_e64 v9, v9, 0, s[4:5]
	s_cselect_b32 s12, s33, s13
	v_cmp_le_i32_e64 s[4:5], s8, v3
	v_cmp_ne_u32_e64 s[8:9], s8, v3
	v_cmp_ge_u32_e64 s[6:7], s36, v2
	s_cselect_b32 s34, 32, 16
	v_mov_b32_e32 v10, s10
	v_cmp_le_i32_e64 s[10:11], s12, v4
	v_cmp_ne_u32_e64 s[12:13], s12, v4
	s_or_b64 s[8:9], s[8:9], vcc
	s_or_b64 s[6:7], s[12:13], s[6:7]
	s_and_b64 s[4:5], s[4:5], s[8:9]
	v_mov_b32_e32 v11, s34
	v_cndmask_b32_e64 v10, v10, 0, s[4:5]
	s_and_b64 s[4:5], s[10:11], s[6:7]
	s_add_i32 s31, s31, 6
	s_add_i32 s21, s21, 6
	s_add_i32 s30, s30, -6
	v_cndmask_b32_e64 v11, v11, 0, s[4:5]
	v_add3_u32 v5, v5, v8, v10
	s_cmp_lg_u32 s30, 0
	v_add3_u32 v7, v7, v9, v11
	s_cbranch_scc1 .LBB0_164
	v_add_u32_e32 v4, v7, v5
	v_ashrrev_i32_e32 v5, 31, v4
	v_lshl_add_u64 v[4:5], v[4:5], 2, s[42:43]
	s_mov_b32 s6, 1
	s_mov_b32 s7, 0
	s_mov_b64 s[4:5], 0
